# prologue adaLN dot products: weight loads of pass i+3 issued while pass i is consumed (loop unrolled by 4, rotating register sets) instead of one round trip per pass
# speedup vs baseline: 1.0101x; 1.0055x over previous
; DI void adaln_item(const Params& p, int item, char* smem) {
;     ...
;     const int col = tid & 31, kg = tid >> 5;
;     float acc[9];
; #pragma unroll
;     for (int r = 0; r < 9; ++r) acc[r] = 0.f;
;     const float* w = p.w_ada + ((size_t)l * 1024 + kg * 128) * 3072 + col0 + col;
; #pragma unroll 8
;     for (int k = 0; k < 128; ++k) {
;         const float wv = w[(size_t)k * 3072];
; #pragma unroll
;         for (int r = 0; r < 9; ++r) acc[r] += sc[r * 1024 + kg * 128 + k] * wv;
;     }
.LBB0_313:
	s_or_b64 exec, exec, s[4:5]
	s_mul_hi_i32 s4, s42, 0x2aaaaaab
	s_lshr_b32 s5, s4, 31
	s_ashr_i32 s4, s4, 4
	s_add_i32 s4, s4, s5
	s_waitcnt lgkmcnt(0)
	s_barrier
	s_load_dwordx2 s[8:9], s[0:1], 0x28
	s_mul_i32 s5, s4, 0x60
	s_sub_i32 s5, s42, s5
	v_ashrrev_i32_e32 v33, 5, v32
	s_lshl_b32 s6, s5, 5
	s_ashr_i32 s5, s4, 31
	v_lshlrev_b32_e32 v0, 7, v33
	s_lshl_b64 s[28:29], s[4:5], 10
	v_ashrrev_i32_e32 v1, 31, v0
	v_lshl_add_u64 v[0:1], s[28:29], 0, v[0:1]
	s_waitcnt lgkmcnt(0)
	v_mov_b64_e32 v[2:3], s[8:9]
	v_mad_u64_u32 v[2:3], s[8:9], v0, s20, v[2:3]
	v_and_b32_e32 v34, 31, v32
	v_mad_i32_i24 v3, v1, s20, v3
	s_ashr_i32 s7, s6, 31
	v_lshl_add_u64 v[0:1], s[6:7], 2, v[2:3]
	v_lshlrev_b32_e32 v192, 2, v34
	v_mov_b32_e32 v58, 0
	v_lshl_add_u64 v[36:37], v[0:1], 0, v[192:193]
	v_lshl_add_u32 v35, v33, 9, 32
	s_mov_b64 s[8:9], 0
	v_mov_b32_e32 v59, v58
	v_mov_b32_e32 v60, v58
	v_mov_b32_e32 v61, v58
	v_mov_b32_e32 v56, v58
	v_mov_b32_e32 v57, v58
	v_mov_b32_e32 v54, v58
	v_mov_b32_e32 v55, v58
	v_mov_b32_e32 v63, v58
	global_load_dword v148, v[36:37], off
	v_add_co_u32_e32 v234, vcc, 0x3000, v36
	v_addc_co_u32_e32 v235, vcc, 0, v37, vcc
	global_load_dword v150, v[234:235], off
	v_add_co_u32_e32 v234, vcc, 0x6000, v36
	v_addc_co_u32_e32 v235, vcc, 0, v37, vcc
	global_load_dword v152, v[234:235], off
	v_add_co_u32_e32 v234, vcc, 0x9000, v36
	v_addc_co_u32_e32 v235, vcc, 0, v37, vcc
	global_load_dword v154, v[234:235], off
	v_add_co_u32_e32 v234, vcc, 0xc000, v36
	v_addc_co_u32_e32 v235, vcc, 0, v37, vcc
	global_load_dword v156, v[234:235], off
	v_add_co_u32_e32 v234, vcc, 0xf000, v36
	v_addc_co_u32_e32 v235, vcc, 0, v37, vcc
	global_load_dword v158, v[234:235], off
	v_add_co_u32_e32 v234, vcc, 0x12000, v36
	v_addc_co_u32_e32 v235, vcc, 0, v37, vcc
	global_load_dword v160, v[234:235], off
	v_add_co_u32_e32 v234, vcc, 0x15000, v36
	v_addc_co_u32_e32 v235, vcc, 0, v37, vcc
	global_load_dword v162, v[234:235], off
	v_add_co_u32_e32 v234, vcc, 0x18000, v36
	v_addc_co_u32_e32 v235, vcc, 0, v37, vcc
	global_load_dword v164, v[234:235], off
	v_add_co_u32_e32 v234, vcc, 0x1b000, v36
	v_addc_co_u32_e32 v235, vcc, 0, v37, vcc
	global_load_dword v166, v[234:235], off
	v_add_co_u32_e32 v234, vcc, 0x1e000, v36
	v_addc_co_u32_e32 v235, vcc, 0, v37, vcc
	global_load_dword v168, v[234:235], off
	v_add_co_u32_e32 v234, vcc, 0x21000, v36
	v_addc_co_u32_e32 v235, vcc, 0, v37, vcc
	global_load_dword v170, v[234:235], off
	v_add_co_u32_e32 v234, vcc, 0x24000, v36
	v_addc_co_u32_e32 v235, vcc, 0, v37, vcc
	global_load_dword v172, v[234:235], off
	v_add_co_u32_e32 v234, vcc, 0x27000, v36
	v_addc_co_u32_e32 v235, vcc, 0, v37, vcc
	global_load_dword v174, v[234:235], off
	v_add_co_u32_e32 v234, vcc, 0x2a000, v36
	v_addc_co_u32_e32 v235, vcc, 0, v37, vcc
	global_load_dword v176, v[234:235], off
	v_add_co_u32_e32 v234, vcc, 0x2d000, v36
	v_addc_co_u32_e32 v235, vcc, 0, v37, vcc
	global_load_dword v178, v[234:235], off
	v_add_co_u32_e32 v234, vcc, 0x30000, v36
	v_addc_co_u32_e32 v235, vcc, 0, v37, vcc
	global_load_dword v180, v[234:235], off
	v_add_co_u32_e32 v234, vcc, 0x33000, v36
	v_addc_co_u32_e32 v235, vcc, 0, v37, vcc
	global_load_dword v182, v[234:235], off
	v_add_co_u32_e32 v234, vcc, 0x36000, v36
	v_addc_co_u32_e32 v235, vcc, 0, v37, vcc
	global_load_dword v184, v[234:235], off
	v_add_co_u32_e32 v234, vcc, 0x39000, v36
	v_addc_co_u32_e32 v235, vcc, 0, v37, vcc
	global_load_dword v186, v[234:235], off
	v_add_co_u32_e32 v234, vcc, 0x3c000, v36
	v_addc_co_u32_e32 v235, vcc, 0, v37, vcc
	global_load_dword v188, v[234:235], off
	v_add_co_u32_e32 v234, vcc, 0x3f000, v36
	v_addc_co_u32_e32 v235, vcc, 0, v37, vcc
	global_load_dword v190, v[234:235], off
	v_add_co_u32_e32 v234, vcc, 0x42000, v36
	v_addc_co_u32_e32 v235, vcc, 0, v37, vcc
	global_load_dword v214, v[234:235], off
	v_add_co_u32_e32 v234, vcc, 0x45000, v36
	v_addc_co_u32_e32 v235, vcc, 0, v37, vcc
	global_load_dword v216, v[234:235], off
.LBB0_314:
	ds_read_b128 v[12:15], v35
	ds_read_b128 v[38:41], v35 offset:16
	ds_read_b128 v[42:45], v35 offset:24576
	ds_read_b128 v[20:23], v35 offset:4096
	ds_read_b128 v[0:3], v35 offset:4112
	ds_read_b128 v[16:19], v35 offset:8192
	ds_read_b128 v[48:51], v35 offset:8208
	ds_read_b128 v[24:27], v35 offset:12288
	ds_read_b128 v[4:7], v35 offset:12304
	ds_read_b128 v[66:69], v35 offset:16384
	ds_read_b128 v[70:73], v35 offset:16400
	ds_read_b128 v[28:31], v35 offset:20480
	ds_read_b128 v[8:11], v35 offset:20496
	s_waitcnt lgkmcnt(12)
	v_mov_b32_e32 v78, v12
	s_waitcnt lgkmcnt(9)
	v_mov_b32_e32 v79, v20
	v_mov_b32_e32 v20, v13
	v_mov_b32_e32 v80, v14
	v_mov_b32_e32 v81, v22
	v_mov_b32_e32 v22, v15
	s_waitcnt lgkmcnt(7)
	v_mov_b32_e32 v82, v16
	s_waitcnt lgkmcnt(5)
	v_mov_b32_e32 v83, v24
	v_mov_b32_e32 v24, v17
	v_mov_b32_e32 v84, v18
	v_mov_b32_e32 v85, v26
	v_mov_b32_e32 v26, v19
	s_waitcnt lgkmcnt(3)
	v_mov_b32_e32 v86, v66
	s_waitcnt lgkmcnt(1)
	v_mov_b32_e32 v87, v28
	v_mov_b32_e32 v28, v67
	v_mov_b32_e32 v88, v68
	v_mov_b32_e32 v89, v30
	v_mov_b32_e32 v30, v69
	ds_read_b128 v[66:69], v35 offset:24592
	ds_read_b128 v[16:19], v35 offset:28672
	ds_read_b128 v[12:15], v35 offset:28688
	v_mov_b32_e32 v46, v48
	v_mov_b32_e32 v47, v4
	v_mov_b32_e32 v4, v49
	s_waitcnt lgkmcnt(2)
	v_mov_b32_e32 v52, v66
	s_waitcnt lgkmcnt(0)
; DI void adaln_item(const Params& p, int item, char* smem) {
;     ...
; #pragma unroll 8
;     for (int k = 0; k < 128; ++k) {
;         const float wv = w[(size_t)k * 3072];
; #pragma unroll
;         for (int r = 0; r < 9; ++r) acc[r] += sc[r * 1024 + kg * 128 + k] * wv;
;     }
	v_mov_b32_e32 v53, v12
	v_mov_b32_e32 v12, v67
	s_add_u32 s100, s8, 0x48000
	s_min_u32 s100, s100, 0x168000
	s_mov_b32 s101, 0
	v_lshl_add_u64 v[66:67], v[36:37], 0, s[100:101]
	v_mov_b32_e32 v48, v68
	v_add_co_u32_e32 v68, vcc, s20, v66
	v_mov_b32_e32 v49, v14
	v_mov_b32_e32 v14, v69
	v_addc_co_u32_e32 v69, vcc, 0, v67, vcc
	s_movk_i32 s5, 0x6000
	v_mov_b32_e32 v90, v42
	v_mov_b32_e32 v42, v38
	v_mov_b32_e32 v38, v40
	v_mov_b32_e32 v40, v50
	v_mov_b32_e32 v50, v70
	v_add_co_u32_e32 v70, vcc, s5, v66
	v_mov_b32_e32 v91, v16
	v_mov_b32_e32 v16, v43
	v_mov_b32_e32 v43, v0
	v_mov_b32_e32 v0, v39
	v_mov_b32_e32 v39, v2
	v_mov_b32_e32 v2, v41
	v_mov_b32_e32 v41, v6
	v_mov_b32_e32 v6, v51
	v_mov_b32_e32 v51, v8
	v_mov_b32_e32 v8, v71
	v_addc_co_u32_e32 v71, vcc, 0, v67, vcc
	s_mov_b32 s5, 0x9000
	v_mov_b32_e32 v76, v44
	v_mov_b32_e32 v44, v72
	v_add_co_u32_e32 v72, vcc, s5, v66
	v_mov_b32_e32 v77, v18
	v_mov_b32_e32 v18, v45
	v_mov_b32_e32 v45, v10
	v_mov_b32_e32 v10, v73
	v_addc_co_u32_e32 v73, vcc, 0, v67, vcc
	s_mov_b32 s5, 0xc000
	v_add_co_u32_e32 v92, vcc, s5, v66
	s_mov_b32 s5, 0xf000
	s_nop 0
	v_addc_co_u32_e32 v93, vcc, 0, v67, vcc
	v_add_co_u32_e32 v94, vcc, s5, v66
	s_mov_b32 s5, 0x12000
	s_nop 0
	v_addc_co_u32_e32 v95, vcc, 0, v67, vcc
	v_add_co_u32_e32 v96, vcc, s5, v66
	s_mov_b32 s5, 0x15000
	s_nop 0
	v_addc_co_u32_e32 v97, vcc, 0, v67, vcc
	v_add_co_u32_e32 v98, vcc, s5, v66
	s_add_u32 s8, s8, 0x18000
	s_nop 0
	v_addc_co_u32_e32 v99, vcc, 0, v67, vcc
	global_load_dword v218, v[66:67], off
	global_load_dword v220, v[68:69], off
	global_load_dword v222, v[70:71], off
	s_nop 0
	global_load_dword v224, v[72:73], off
	s_nop 0
	global_load_dword v226, v[92:93], off
	global_load_dword v228, v[94:95], off
	global_load_dword v230, v[96:97], off
	global_load_dword v232, v[98:99], off
	s_addc_u32 s9, s9, 0
	s_cmp_eq_u32 s8, 0x180000
	s_waitcnt vmcnt(24)
	v_pk_fma_f32 v[58:59], v[148:149], v[78:79], v[58:59] op_sel_hi:[0,1,1]
	v_pk_fma_f32 v[20:21], v[150:151], v[20:21], v[58:59] op_sel_hi:[0,1,1]
	v_pk_fma_f32 v[20:21], v[152:153], v[80:81], v[20:21] op_sel_hi:[0,1,1]
	v_pk_fma_f32 v[58:59], v[154:155], v[22:23], v[20:21] op_sel_hi:[0,1,1]
	v_pk_fma_f32 v[20:21], v[148:149], v[82:83], v[60:61] op_sel_hi:[0,1,1]
	v_pk_fma_f32 v[20:21], v[150:151], v[24:25], v[20:21] op_sel_hi:[0,1,1]
	v_pk_fma_f32 v[20:21], v[152:153], v[84:85], v[20:21] op_sel_hi:[0,1,1]
	v_pk_fma_f32 v[60:61], v[154:155], v[26:27], v[20:21] op_sel_hi:[0,1,1]
	v_pk_fma_f32 v[20:21], v[148:149], v[86:87], v[56:57] op_sel_hi:[0,1,1]
	v_pk_fma_f32 v[20:21], v[150:151], v[28:29], v[20:21] op_sel_hi:[0,1,1]
	v_pk_fma_f32 v[20:21], v[152:153], v[88:89], v[20:21] op_sel_hi:[0,1,1]
	v_pk_fma_f32 v[28:29], v[154:155], v[30:31], v[20:21] op_sel_hi:[0,1,1]
	ds_read_b128 v[24:27], v35 offset:32768
	ds_read_b128 v[20:23], v35 offset:32784
	v_pk_fma_f32 v[30:31], v[148:149], v[90:91], v[54:55] op_sel_hi:[0,1,1]
	v_pk_fma_f32 v[16:17], v[150:151], v[16:17], v[30:31] op_sel_hi:[0,1,1]
	v_pk_fma_f32 v[16:17], v[152:153], v[76:77], v[16:17] op_sel_hi:[0,1,1]
	s_waitcnt lgkmcnt(1)
	v_fmac_f32_e32 v63, v148, v24
	v_fmac_f32_e32 v63, v150, v25
	v_fmac_f32_e32 v63, v152, v26
	v_pk_fma_f32 v[16:17], v[154:155], v[18:19], v[16:17] op_sel_hi:[0,1,1]
	v_fmac_f32_e32 v63, v154, v27
	v_pk_fma_f32 v[18:19], v[156:157], v[42:43], v[58:59] op_sel_hi:[0,1,1]
	v_pk_fma_f32 v[24:25], v[156:157], v[46:47], v[60:61] op_sel_hi:[0,1,1]
	v_pk_fma_f32 v[26:27], v[156:157], v[50:51], v[28:29] op_sel_hi:[0,1,1]
	v_pk_fma_f32 v[16:17], v[156:157], v[52:53], v[16:17] op_sel_hi:[0,1,1]
	s_waitcnt lgkmcnt(0)
	v_fmac_f32_e32 v63, v156, v20
	v_pk_fma_f32 v[0:1], v[158:159], v[0:1], v[18:19] op_sel_hi:[0,1,1]
	v_pk_fma_f32 v[4:5], v[158:159], v[4:5], v[24:25] op_sel_hi:[0,1,1]
	v_pk_fma_f32 v[8:9], v[158:159], v[8:9], v[26:27] op_sel_hi:[0,1,1]
	v_pk_fma_f32 v[12:13], v[158:159], v[12:13], v[16:17] op_sel_hi:[0,1,1]
	v_fmac_f32_e32 v63, v158, v21
	v_pk_fma_f32 v[0:1], v[160:161], v[38:39], v[0:1] op_sel_hi:[0,1,1]
	v_pk_fma_f32 v[4:5], v[160:161], v[40:41], v[4:5] op_sel_hi:[0,1,1]
	v_pk_fma_f32 v[8:9], v[160:161], v[44:45], v[8:9] op_sel_hi:[0,1,1]
	v_pk_fma_f32 v[12:13], v[160:161], v[48:49], v[12:13] op_sel_hi:[0,1,1]
	v_fmac_f32_e32 v63, v160, v22
	v_add_u32_e32 v35, 32, v35
	v_pk_fma_f32 v[58:59], v[162:163], v[2:3], v[0:1] op_sel_hi:[0,1,1]
	v_pk_fma_f32 v[60:61], v[162:163], v[6:7], v[4:5] op_sel_hi:[0,1,1]
	v_pk_fma_f32 v[56:57], v[162:163], v[10:11], v[8:9] op_sel_hi:[0,1,1]
	v_pk_fma_f32 v[54:55], v[162:163], v[14:15], v[12:13] op_sel_hi:[0,1,1]
	v_fmac_f32_e32 v63, v162, v23
	ds_read_b128 v[12:15], v35
	ds_read_b128 v[38:41], v35 offset:16
	ds_read_b128 v[42:45], v35 offset:24576
	ds_read_b128 v[20:23], v35 offset:4096
	ds_read_b128 v[0:3], v35 offset:4112
	ds_read_b128 v[16:19], v35 offset:8192
	ds_read_b128 v[48:51], v35 offset:8208
	ds_read_b128 v[24:27], v35 offset:12288
	ds_read_b128 v[4:7], v35 offset:12304
	ds_read_b128 v[66:69], v35 offset:16384
	ds_read_b128 v[70:73], v35 offset:16400
	ds_read_b128 v[28:31], v35 offset:20480
	ds_read_b128 v[8:11], v35 offset:20496
	s_waitcnt lgkmcnt(12)
	v_mov_b32_e32 v78, v12
	s_waitcnt lgkmcnt(9)
	v_mov_b32_e32 v79, v20
	v_mov_b32_e32 v20, v13
	v_mov_b32_e32 v80, v14
	v_mov_b32_e32 v81, v22
	v_mov_b32_e32 v22, v15
	s_waitcnt lgkmcnt(7)
	v_mov_b32_e32 v82, v16
	s_waitcnt lgkmcnt(5)
	v_mov_b32_e32 v83, v24
	v_mov_b32_e32 v24, v17
	v_mov_b32_e32 v84, v18
	v_mov_b32_e32 v85, v26
	v_mov_b32_e32 v26, v19
	s_waitcnt lgkmcnt(3)
	v_mov_b32_e32 v86, v66
	s_waitcnt lgkmcnt(1)
; DI void adaln_item(const Params& p, int item, char* smem) {
;     ...
; #pragma unroll 8
;     for (int k = 0; k < 128; ++k) {
;         const float wv = w[(size_t)k * 3072];
; #pragma unroll
;         for (int r = 0; r < 9; ++r) acc[r] += sc[r * 1024 + kg * 128 + k] * wv;
;     }
	v_mov_b32_e32 v87, v28
	v_mov_b32_e32 v28, v67
	v_mov_b32_e32 v88, v68
	v_mov_b32_e32 v89, v30
	v_mov_b32_e32 v30, v69
	ds_read_b128 v[66:69], v35 offset:24592
	ds_read_b128 v[16:19], v35 offset:28672
	ds_read_b128 v[12:15], v35 offset:28688
	v_mov_b32_e32 v46, v48
	v_mov_b32_e32 v47, v4
	v_mov_b32_e32 v4, v49
	s_waitcnt lgkmcnt(2)
	v_mov_b32_e32 v52, v66
	s_waitcnt lgkmcnt(0)
	v_mov_b32_e32 v53, v12
	v_mov_b32_e32 v12, v67
	s_add_u32 s100, s8, 0x48000
	s_min_u32 s100, s100, 0x168000
	s_mov_b32 s101, 0
	v_lshl_add_u64 v[66:67], v[36:37], 0, s[100:101]
	v_mov_b32_e32 v48, v68
	v_add_co_u32_e32 v68, vcc, s20, v66
	v_mov_b32_e32 v49, v14
	v_mov_b32_e32 v14, v69
	v_addc_co_u32_e32 v69, vcc, 0, v67, vcc
	s_movk_i32 s5, 0x6000
	v_mov_b32_e32 v90, v42
	v_mov_b32_e32 v42, v38
	v_mov_b32_e32 v38, v40
	v_mov_b32_e32 v40, v50
	v_mov_b32_e32 v50, v70
	v_add_co_u32_e32 v70, vcc, s5, v66
	v_mov_b32_e32 v91, v16
	v_mov_b32_e32 v16, v43
	v_mov_b32_e32 v43, v0
	v_mov_b32_e32 v0, v39
	v_mov_b32_e32 v39, v2
	v_mov_b32_e32 v2, v41
	v_mov_b32_e32 v41, v6
	v_mov_b32_e32 v6, v51
	v_mov_b32_e32 v51, v8
	v_mov_b32_e32 v8, v71
	v_addc_co_u32_e32 v71, vcc, 0, v67, vcc
	s_mov_b32 s5, 0x9000
	v_mov_b32_e32 v76, v44
	v_mov_b32_e32 v44, v72
	v_add_co_u32_e32 v72, vcc, s5, v66
	v_mov_b32_e32 v77, v18
	v_mov_b32_e32 v18, v45
	v_mov_b32_e32 v45, v10
	v_mov_b32_e32 v10, v73
	v_addc_co_u32_e32 v73, vcc, 0, v67, vcc
	s_mov_b32 s5, 0xc000
	v_add_co_u32_e32 v92, vcc, s5, v66
	s_mov_b32 s5, 0xf000
	s_nop 0
	v_addc_co_u32_e32 v93, vcc, 0, v67, vcc
	v_add_co_u32_e32 v94, vcc, s5, v66
	s_mov_b32 s5, 0x12000
	s_nop 0
	v_addc_co_u32_e32 v95, vcc, 0, v67, vcc
	v_add_co_u32_e32 v96, vcc, s5, v66
	s_mov_b32 s5, 0x15000
	s_nop 0
	v_addc_co_u32_e32 v97, vcc, 0, v67, vcc
	v_add_co_u32_e32 v98, vcc, s5, v66
	s_add_u32 s8, s8, 0x18000
	s_nop 0
	v_addc_co_u32_e32 v99, vcc, 0, v67, vcc
	global_load_dword v148, v[66:67], off
	global_load_dword v150, v[68:69], off
	global_load_dword v152, v[70:71], off
	s_nop 0
	global_load_dword v154, v[72:73], off
	s_nop 0
	global_load_dword v156, v[92:93], off
	global_load_dword v158, v[94:95], off
	global_load_dword v160, v[96:97], off
	global_load_dword v162, v[98:99], off
	s_addc_u32 s9, s9, 0
	s_cmp_eq_u32 s8, 0x180000
	s_waitcnt vmcnt(24)
	v_pk_fma_f32 v[58:59], v[164:165], v[78:79], v[58:59] op_sel_hi:[0,1,1]
	v_pk_fma_f32 v[20:21], v[166:167], v[20:21], v[58:59] op_sel_hi:[0,1,1]
	v_pk_fma_f32 v[20:21], v[168:169], v[80:81], v[20:21] op_sel_hi:[0,1,1]
	v_pk_fma_f32 v[58:59], v[170:171], v[22:23], v[20:21] op_sel_hi:[0,1,1]
	v_pk_fma_f32 v[20:21], v[164:165], v[82:83], v[60:61] op_sel_hi:[0,1,1]
	v_pk_fma_f32 v[20:21], v[166:167], v[24:25], v[20:21] op_sel_hi:[0,1,1]
	v_pk_fma_f32 v[20:21], v[168:169], v[84:85], v[20:21] op_sel_hi:[0,1,1]
	v_pk_fma_f32 v[60:61], v[170:171], v[26:27], v[20:21] op_sel_hi:[0,1,1]
	v_pk_fma_f32 v[20:21], v[164:165], v[86:87], v[56:57] op_sel_hi:[0,1,1]
	v_pk_fma_f32 v[20:21], v[166:167], v[28:29], v[20:21] op_sel_hi:[0,1,1]
	v_pk_fma_f32 v[20:21], v[168:169], v[88:89], v[20:21] op_sel_hi:[0,1,1]
	v_pk_fma_f32 v[28:29], v[170:171], v[30:31], v[20:21] op_sel_hi:[0,1,1]
	ds_read_b128 v[24:27], v35 offset:32768
	ds_read_b128 v[20:23], v35 offset:32784
	v_pk_fma_f32 v[30:31], v[164:165], v[90:91], v[54:55] op_sel_hi:[0,1,1]
	v_pk_fma_f32 v[16:17], v[166:167], v[16:17], v[30:31] op_sel_hi:[0,1,1]
	v_pk_fma_f32 v[16:17], v[168:169], v[76:77], v[16:17] op_sel_hi:[0,1,1]
	s_waitcnt lgkmcnt(1)
	v_fmac_f32_e32 v63, v164, v24
	v_fmac_f32_e32 v63, v166, v25
	v_fmac_f32_e32 v63, v168, v26
	v_pk_fma_f32 v[16:17], v[170:171], v[18:19], v[16:17] op_sel_hi:[0,1,1]
	v_fmac_f32_e32 v63, v170, v27
	v_pk_fma_f32 v[18:19], v[172:173], v[42:43], v[58:59] op_sel_hi:[0,1,1]
	v_pk_fma_f32 v[24:25], v[172:173], v[46:47], v[60:61] op_sel_hi:[0,1,1]
	v_pk_fma_f32 v[26:27], v[172:173], v[50:51], v[28:29] op_sel_hi:[0,1,1]
	v_pk_fma_f32 v[16:17], v[172:173], v[52:53], v[16:17] op_sel_hi:[0,1,1]
	s_waitcnt lgkmcnt(0)
	v_fmac_f32_e32 v63, v172, v20
	v_pk_fma_f32 v[0:1], v[174:175], v[0:1], v[18:19] op_sel_hi:[0,1,1]
	v_pk_fma_f32 v[4:5], v[174:175], v[4:5], v[24:25] op_sel_hi:[0,1,1]
	v_pk_fma_f32 v[8:9], v[174:175], v[8:9], v[26:27] op_sel_hi:[0,1,1]
	v_pk_fma_f32 v[12:13], v[174:175], v[12:13], v[16:17] op_sel_hi:[0,1,1]
	v_fmac_f32_e32 v63, v174, v21
	v_pk_fma_f32 v[0:1], v[176:177], v[38:39], v[0:1] op_sel_hi:[0,1,1]
	v_pk_fma_f32 v[4:5], v[176:177], v[40:41], v[4:5] op_sel_hi:[0,1,1]
	v_pk_fma_f32 v[8:9], v[176:177], v[44:45], v[8:9] op_sel_hi:[0,1,1]
	v_pk_fma_f32 v[12:13], v[176:177], v[48:49], v[12:13] op_sel_hi:[0,1,1]
	v_fmac_f32_e32 v63, v176, v22
	v_add_u32_e32 v35, 32, v35
	v_pk_fma_f32 v[58:59], v[178:179], v[2:3], v[0:1] op_sel_hi:[0,1,1]
	v_pk_fma_f32 v[60:61], v[178:179], v[6:7], v[4:5] op_sel_hi:[0,1,1]
	v_pk_fma_f32 v[56:57], v[178:179], v[10:11], v[8:9] op_sel_hi:[0,1,1]
	v_pk_fma_f32 v[54:55], v[178:179], v[14:15], v[12:13] op_sel_hi:[0,1,1]
	v_fmac_f32_e32 v63, v178, v23
	ds_read_b128 v[12:15], v35
	ds_read_b128 v[38:41], v35 offset:16
	ds_read_b128 v[42:45], v35 offset:24576
	ds_read_b128 v[20:23], v35 offset:4096
	ds_read_b128 v[0:3], v35 offset:4112
	ds_read_b128 v[16:19], v35 offset:8192
	ds_read_b128 v[48:51], v35 offset:8208
	ds_read_b128 v[24:27], v35 offset:12288
	ds_read_b128 v[4:7], v35 offset:12304
	ds_read_b128 v[66:69], v35 offset:16384
	ds_read_b128 v[70:73], v35 offset:16400
	ds_read_b128 v[28:31], v35 offset:20480
	ds_read_b128 v[8:11], v35 offset:20496
	s_waitcnt lgkmcnt(12)
	v_mov_b32_e32 v78, v12
	s_waitcnt lgkmcnt(9)
	v_mov_b32_e32 v79, v20
	v_mov_b32_e32 v20, v13
	v_mov_b32_e32 v80, v14
	v_mov_b32_e32 v81, v22
	v_mov_b32_e32 v22, v15
	s_waitcnt lgkmcnt(7)
; DI void adaln_item(const Params& p, int item, char* smem) {
;     ...
; #pragma unroll 8
;     for (int k = 0; k < 128; ++k) {
;         const float wv = w[(size_t)k * 3072];
; #pragma unroll
;         for (int r = 0; r < 9; ++r) acc[r] += sc[r * 1024 + kg * 128 + k] * wv;
;     }
	v_mov_b32_e32 v82, v16
	s_waitcnt lgkmcnt(5)
	v_mov_b32_e32 v83, v24
	v_mov_b32_e32 v24, v17
	v_mov_b32_e32 v84, v18
	v_mov_b32_e32 v85, v26
	v_mov_b32_e32 v26, v19
	s_waitcnt lgkmcnt(3)
	v_mov_b32_e32 v86, v66
	s_waitcnt lgkmcnt(1)
	v_mov_b32_e32 v87, v28
	v_mov_b32_e32 v28, v67
	v_mov_b32_e32 v88, v68
	v_mov_b32_e32 v89, v30
	v_mov_b32_e32 v30, v69
	ds_read_b128 v[66:69], v35 offset:24592
	ds_read_b128 v[16:19], v35 offset:28672
	ds_read_b128 v[12:15], v35 offset:28688
	v_mov_b32_e32 v46, v48
	v_mov_b32_e32 v47, v4
	v_mov_b32_e32 v4, v49
	s_waitcnt lgkmcnt(2)
	v_mov_b32_e32 v52, v66
	s_waitcnt lgkmcnt(0)
	v_mov_b32_e32 v53, v12
	v_mov_b32_e32 v12, v67
	s_add_u32 s100, s8, 0x48000
	s_min_u32 s100, s100, 0x168000
	s_mov_b32 s101, 0
	v_lshl_add_u64 v[66:67], v[36:37], 0, s[100:101]
	v_mov_b32_e32 v48, v68
	v_add_co_u32_e32 v68, vcc, s20, v66
	v_mov_b32_e32 v49, v14
	v_mov_b32_e32 v14, v69
	v_addc_co_u32_e32 v69, vcc, 0, v67, vcc
	s_movk_i32 s5, 0x6000
	v_mov_b32_e32 v90, v42
	v_mov_b32_e32 v42, v38
	v_mov_b32_e32 v38, v40
	v_mov_b32_e32 v40, v50
	v_mov_b32_e32 v50, v70
	v_add_co_u32_e32 v70, vcc, s5, v66
	v_mov_b32_e32 v91, v16
	v_mov_b32_e32 v16, v43
	v_mov_b32_e32 v43, v0
	v_mov_b32_e32 v0, v39
	v_mov_b32_e32 v39, v2
	v_mov_b32_e32 v2, v41
	v_mov_b32_e32 v41, v6
	v_mov_b32_e32 v6, v51
	v_mov_b32_e32 v51, v8
	v_mov_b32_e32 v8, v71
	v_addc_co_u32_e32 v71, vcc, 0, v67, vcc
	s_mov_b32 s5, 0x9000
	v_mov_b32_e32 v76, v44
	v_mov_b32_e32 v44, v72
	v_add_co_u32_e32 v72, vcc, s5, v66
	v_mov_b32_e32 v77, v18
	v_mov_b32_e32 v18, v45
	v_mov_b32_e32 v45, v10
	v_mov_b32_e32 v10, v73
	v_addc_co_u32_e32 v73, vcc, 0, v67, vcc
	s_mov_b32 s5, 0xc000
	v_add_co_u32_e32 v92, vcc, s5, v66
	s_mov_b32 s5, 0xf000
	s_nop 0
	v_addc_co_u32_e32 v93, vcc, 0, v67, vcc
	v_add_co_u32_e32 v94, vcc, s5, v66
	s_mov_b32 s5, 0x12000
	s_nop 0
	v_addc_co_u32_e32 v95, vcc, 0, v67, vcc
	v_add_co_u32_e32 v96, vcc, s5, v66
	s_mov_b32 s5, 0x15000
	s_nop 0
	v_addc_co_u32_e32 v97, vcc, 0, v67, vcc
	v_add_co_u32_e32 v98, vcc, s5, v66
	s_add_u32 s8, s8, 0x18000
	s_nop 0
	v_addc_co_u32_e32 v99, vcc, 0, v67, vcc
	global_load_dword v164, v[66:67], off
	global_load_dword v166, v[68:69], off
	global_load_dword v168, v[70:71], off
	s_nop 0
	global_load_dword v170, v[72:73], off
	s_nop 0
	global_load_dword v172, v[92:93], off
	global_load_dword v174, v[94:95], off
	global_load_dword v176, v[96:97], off
	global_load_dword v178, v[98:99], off
	s_addc_u32 s9, s9, 0
	s_cmp_eq_u32 s8, 0x180000
	s_waitcnt vmcnt(24)
	v_pk_fma_f32 v[58:59], v[180:181], v[78:79], v[58:59] op_sel_hi:[0,1,1]
	v_pk_fma_f32 v[20:21], v[182:183], v[20:21], v[58:59] op_sel_hi:[0,1,1]
	v_pk_fma_f32 v[20:21], v[184:185], v[80:81], v[20:21] op_sel_hi:[0,1,1]
	v_pk_fma_f32 v[58:59], v[186:187], v[22:23], v[20:21] op_sel_hi:[0,1,1]
	v_pk_fma_f32 v[20:21], v[180:181], v[82:83], v[60:61] op_sel_hi:[0,1,1]
	v_pk_fma_f32 v[20:21], v[182:183], v[24:25], v[20:21] op_sel_hi:[0,1,1]
	v_pk_fma_f32 v[20:21], v[184:185], v[84:85], v[20:21] op_sel_hi:[0,1,1]
	v_pk_fma_f32 v[60:61], v[186:187], v[26:27], v[20:21] op_sel_hi:[0,1,1]
	v_pk_fma_f32 v[20:21], v[180:181], v[86:87], v[56:57] op_sel_hi:[0,1,1]
	v_pk_fma_f32 v[20:21], v[182:183], v[28:29], v[20:21] op_sel_hi:[0,1,1]
	v_pk_fma_f32 v[20:21], v[184:185], v[88:89], v[20:21] op_sel_hi:[0,1,1]
	v_pk_fma_f32 v[28:29], v[186:187], v[30:31], v[20:21] op_sel_hi:[0,1,1]
	ds_read_b128 v[24:27], v35 offset:32768
	ds_read_b128 v[20:23], v35 offset:32784
	v_pk_fma_f32 v[30:31], v[180:181], v[90:91], v[54:55] op_sel_hi:[0,1,1]
	v_pk_fma_f32 v[16:17], v[182:183], v[16:17], v[30:31] op_sel_hi:[0,1,1]
	v_pk_fma_f32 v[16:17], v[184:185], v[76:77], v[16:17] op_sel_hi:[0,1,1]
	s_waitcnt lgkmcnt(1)
	v_fmac_f32_e32 v63, v180, v24
	v_fmac_f32_e32 v63, v182, v25
	v_fmac_f32_e32 v63, v184, v26
	v_pk_fma_f32 v[16:17], v[186:187], v[18:19], v[16:17] op_sel_hi:[0,1,1]
	v_fmac_f32_e32 v63, v186, v27
	v_pk_fma_f32 v[18:19], v[188:189], v[42:43], v[58:59] op_sel_hi:[0,1,1]
	v_pk_fma_f32 v[24:25], v[188:189], v[46:47], v[60:61] op_sel_hi:[0,1,1]
	v_pk_fma_f32 v[26:27], v[188:189], v[50:51], v[28:29] op_sel_hi:[0,1,1]
	v_pk_fma_f32 v[16:17], v[188:189], v[52:53], v[16:17] op_sel_hi:[0,1,1]
	s_waitcnt lgkmcnt(0)
	v_fmac_f32_e32 v63, v188, v20
	v_pk_fma_f32 v[0:1], v[190:191], v[0:1], v[18:19] op_sel_hi:[0,1,1]
	v_pk_fma_f32 v[4:5], v[190:191], v[4:5], v[24:25] op_sel_hi:[0,1,1]
	v_pk_fma_f32 v[8:9], v[190:191], v[8:9], v[26:27] op_sel_hi:[0,1,1]
	v_pk_fma_f32 v[12:13], v[190:191], v[12:13], v[16:17] op_sel_hi:[0,1,1]
	v_fmac_f32_e32 v63, v190, v21
	v_pk_fma_f32 v[0:1], v[214:215], v[38:39], v[0:1] op_sel_hi:[0,1,1]
	v_pk_fma_f32 v[4:5], v[214:215], v[40:41], v[4:5] op_sel_hi:[0,1,1]
	v_pk_fma_f32 v[8:9], v[214:215], v[44:45], v[8:9] op_sel_hi:[0,1,1]
	v_pk_fma_f32 v[12:13], v[214:215], v[48:49], v[12:13] op_sel_hi:[0,1,1]
	v_fmac_f32_e32 v63, v214, v22
	v_add_u32_e32 v35, 32, v35
	v_pk_fma_f32 v[58:59], v[216:217], v[2:3], v[0:1] op_sel_hi:[0,1,1]
	v_pk_fma_f32 v[60:61], v[216:217], v[6:7], v[4:5] op_sel_hi:[0,1,1]
	v_pk_fma_f32 v[56:57], v[216:217], v[10:11], v[8:9] op_sel_hi:[0,1,1]
	v_pk_fma_f32 v[54:55], v[216:217], v[14:15], v[12:13] op_sel_hi:[0,1,1]
	v_fmac_f32_e32 v63, v216, v23
	ds_read_b128 v[12:15], v35
	ds_read_b128 v[38:41], v35 offset:16
	ds_read_b128 v[42:45], v35 offset:24576
	ds_read_b128 v[20:23], v35 offset:4096
	ds_read_b128 v[0:3], v35 offset:4112
	ds_read_b128 v[16:19], v35 offset:8192
	ds_read_b128 v[48:51], v35 offset:8208
	ds_read_b128 v[24:27], v35 offset:12288
	ds_read_b128 v[4:7], v35 offset:12304
	ds_read_b128 v[66:69], v35 offset:16384
	ds_read_b128 v[70:73], v35 offset:16400
	ds_read_b128 v[28:31], v35 offset:20480
	ds_read_b128 v[8:11], v35 offset:20496
	s_waitcnt lgkmcnt(12)
; DI void adaln_item(const Params& p, int item, char* smem) {
;     ...
; #pragma unroll 8
;     for (int k = 0; k < 128; ++k) {
;         const float wv = w[(size_t)k * 3072];
; #pragma unroll
;         for (int r = 0; r < 9; ++r) acc[r] += sc[r * 1024 + kg * 128 + k] * wv;
;     }
; #pragma unroll
;     for (int r = 0; r < 9; ++r) red[(kg * 9 + r) * 32 + col] = acc[r];
;     __syncthreads();
;     for (int i = tid; i < 9 * 32; i += 256) {
;         const int r = i >> 5, cc = i & 31;
;         float s = 0.f;
; #pragma unroll
;         for (int g = 0; g < 8; ++g) s += red[(g * 9 + r) * 32 + cc];
;         p.mod[((size_t)l * 9 + r) * 3072 + col0 + cc] = s + p.b_ada[l * 3072 + col0 + cc];
	v_mov_b32_e32 v78, v12
	s_waitcnt lgkmcnt(9)
	v_mov_b32_e32 v79, v20
	v_mov_b32_e32 v20, v13
	v_mov_b32_e32 v80, v14
	v_mov_b32_e32 v81, v22
	v_mov_b32_e32 v22, v15
	s_waitcnt lgkmcnt(7)
	v_mov_b32_e32 v82, v16
	s_waitcnt lgkmcnt(5)
	v_mov_b32_e32 v83, v24
	v_mov_b32_e32 v24, v17
	v_mov_b32_e32 v84, v18
	v_mov_b32_e32 v85, v26
	v_mov_b32_e32 v26, v19
	s_waitcnt lgkmcnt(3)
	v_mov_b32_e32 v86, v66
	s_waitcnt lgkmcnt(1)
	v_mov_b32_e32 v87, v28
	v_mov_b32_e32 v28, v67
	v_mov_b32_e32 v88, v68
	v_mov_b32_e32 v89, v30
	v_mov_b32_e32 v30, v69
	ds_read_b128 v[66:69], v35 offset:24592
	ds_read_b128 v[16:19], v35 offset:28672
	ds_read_b128 v[12:15], v35 offset:28688
	v_mov_b32_e32 v46, v48
	v_mov_b32_e32 v47, v4
	v_mov_b32_e32 v4, v49
	s_waitcnt lgkmcnt(2)
	v_mov_b32_e32 v52, v66
	s_waitcnt lgkmcnt(0)
	v_mov_b32_e32 v53, v12
	v_mov_b32_e32 v12, v67
	s_add_u32 s100, s8, 0x48000
	s_min_u32 s100, s100, 0x168000
	s_mov_b32 s101, 0
	v_lshl_add_u64 v[66:67], v[36:37], 0, s[100:101]
	v_mov_b32_e32 v48, v68
	v_add_co_u32_e32 v68, vcc, s20, v66
	v_mov_b32_e32 v49, v14
	v_mov_b32_e32 v14, v69
	v_addc_co_u32_e32 v69, vcc, 0, v67, vcc
	s_movk_i32 s5, 0x6000
	v_mov_b32_e32 v90, v42
	v_mov_b32_e32 v42, v38
	v_mov_b32_e32 v38, v40
	v_mov_b32_e32 v40, v50
	v_mov_b32_e32 v50, v70
	v_add_co_u32_e32 v70, vcc, s5, v66
	v_mov_b32_e32 v91, v16
	v_mov_b32_e32 v16, v43
	v_mov_b32_e32 v43, v0
	v_mov_b32_e32 v0, v39
	v_mov_b32_e32 v39, v2
	v_mov_b32_e32 v2, v41
	v_mov_b32_e32 v41, v6
	v_mov_b32_e32 v6, v51
	v_mov_b32_e32 v51, v8
	v_mov_b32_e32 v8, v71
	v_addc_co_u32_e32 v71, vcc, 0, v67, vcc
	s_mov_b32 s5, 0x9000
	v_mov_b32_e32 v76, v44
	v_mov_b32_e32 v44, v72
	v_add_co_u32_e32 v72, vcc, s5, v66
	v_mov_b32_e32 v77, v18
	v_mov_b32_e32 v18, v45
	v_mov_b32_e32 v45, v10
	v_mov_b32_e32 v10, v73
	v_addc_co_u32_e32 v73, vcc, 0, v67, vcc
	s_mov_b32 s5, 0xc000
	v_add_co_u32_e32 v92, vcc, s5, v66
	s_mov_b32 s5, 0xf000
	s_nop 0
	v_addc_co_u32_e32 v93, vcc, 0, v67, vcc
	v_add_co_u32_e32 v94, vcc, s5, v66
	s_mov_b32 s5, 0x12000
	s_nop 0
	v_addc_co_u32_e32 v95, vcc, 0, v67, vcc
	v_add_co_u32_e32 v96, vcc, s5, v66
	s_mov_b32 s5, 0x15000
	s_nop 0
	v_addc_co_u32_e32 v97, vcc, 0, v67, vcc
	v_add_co_u32_e32 v98, vcc, s5, v66
	s_add_u32 s8, s8, 0x18000
	s_nop 0
	v_addc_co_u32_e32 v99, vcc, 0, v67, vcc
	global_load_dword v180, v[66:67], off
	global_load_dword v182, v[68:69], off
	global_load_dword v184, v[70:71], off
	s_nop 0
	global_load_dword v186, v[72:73], off
	s_nop 0
	global_load_dword v188, v[92:93], off
	global_load_dword v190, v[94:95], off
	global_load_dword v214, v[96:97], off
	global_load_dword v216, v[98:99], off
	s_addc_u32 s9, s9, 0
	s_cmp_eq_u32 s8, 0x180000
	s_waitcnt vmcnt(24)
	v_pk_fma_f32 v[58:59], v[218:219], v[78:79], v[58:59] op_sel_hi:[0,1,1]
	v_pk_fma_f32 v[20:21], v[220:221], v[20:21], v[58:59] op_sel_hi:[0,1,1]
	v_pk_fma_f32 v[20:21], v[222:223], v[80:81], v[20:21] op_sel_hi:[0,1,1]
	v_pk_fma_f32 v[58:59], v[224:225], v[22:23], v[20:21] op_sel_hi:[0,1,1]
	v_pk_fma_f32 v[20:21], v[218:219], v[82:83], v[60:61] op_sel_hi:[0,1,1]
	v_pk_fma_f32 v[20:21], v[220:221], v[24:25], v[20:21] op_sel_hi:[0,1,1]
	v_pk_fma_f32 v[20:21], v[222:223], v[84:85], v[20:21] op_sel_hi:[0,1,1]
	v_pk_fma_f32 v[60:61], v[224:225], v[26:27], v[20:21] op_sel_hi:[0,1,1]
	v_pk_fma_f32 v[20:21], v[218:219], v[86:87], v[56:57] op_sel_hi:[0,1,1]
	v_pk_fma_f32 v[20:21], v[220:221], v[28:29], v[20:21] op_sel_hi:[0,1,1]
	v_pk_fma_f32 v[20:21], v[222:223], v[88:89], v[20:21] op_sel_hi:[0,1,1]
	v_pk_fma_f32 v[28:29], v[224:225], v[30:31], v[20:21] op_sel_hi:[0,1,1]
	ds_read_b128 v[24:27], v35 offset:32768
	ds_read_b128 v[20:23], v35 offset:32784
	v_pk_fma_f32 v[30:31], v[218:219], v[90:91], v[54:55] op_sel_hi:[0,1,1]
	v_pk_fma_f32 v[16:17], v[220:221], v[16:17], v[30:31] op_sel_hi:[0,1,1]
	v_pk_fma_f32 v[16:17], v[222:223], v[76:77], v[16:17] op_sel_hi:[0,1,1]
	s_waitcnt lgkmcnt(1)
	v_fmac_f32_e32 v63, v218, v24
	v_fmac_f32_e32 v63, v220, v25
	v_fmac_f32_e32 v63, v222, v26
	v_pk_fma_f32 v[16:17], v[224:225], v[18:19], v[16:17] op_sel_hi:[0,1,1]
	v_fmac_f32_e32 v63, v224, v27
	v_pk_fma_f32 v[18:19], v[226:227], v[42:43], v[58:59] op_sel_hi:[0,1,1]
	v_pk_fma_f32 v[24:25], v[226:227], v[46:47], v[60:61] op_sel_hi:[0,1,1]
	v_pk_fma_f32 v[26:27], v[226:227], v[50:51], v[28:29] op_sel_hi:[0,1,1]
	v_pk_fma_f32 v[16:17], v[226:227], v[52:53], v[16:17] op_sel_hi:[0,1,1]
	s_waitcnt lgkmcnt(0)
	v_fmac_f32_e32 v63, v226, v20
	v_pk_fma_f32 v[0:1], v[228:229], v[0:1], v[18:19] op_sel_hi:[0,1,1]
	v_pk_fma_f32 v[4:5], v[228:229], v[4:5], v[24:25] op_sel_hi:[0,1,1]
	v_pk_fma_f32 v[8:9], v[228:229], v[8:9], v[26:27] op_sel_hi:[0,1,1]
	v_pk_fma_f32 v[12:13], v[228:229], v[12:13], v[16:17] op_sel_hi:[0,1,1]
	v_fmac_f32_e32 v63, v228, v21
	v_pk_fma_f32 v[0:1], v[230:231], v[38:39], v[0:1] op_sel_hi:[0,1,1]
	v_pk_fma_f32 v[4:5], v[230:231], v[40:41], v[4:5] op_sel_hi:[0,1,1]
	v_pk_fma_f32 v[8:9], v[230:231], v[44:45], v[8:9] op_sel_hi:[0,1,1]
	v_pk_fma_f32 v[12:13], v[230:231], v[48:49], v[12:13] op_sel_hi:[0,1,1]
	v_fmac_f32_e32 v63, v230, v22
	v_add_u32_e32 v35, 32, v35
	v_pk_fma_f32 v[58:59], v[232:233], v[2:3], v[0:1] op_sel_hi:[0,1,1]
	v_pk_fma_f32 v[60:61], v[232:233], v[6:7], v[4:5] op_sel_hi:[0,1,1]
	v_pk_fma_f32 v[56:57], v[232:233], v[10:11], v[8:9] op_sel_hi:[0,1,1]
	v_pk_fma_f32 v[54:55], v[232:233], v[14:15], v[12:13] op_sel_hi:[0,1,1]
	v_fmac_f32_e32 v63, v232, v23
	s_cbranch_scc0 .LBB0_314
	s_waitcnt vmcnt(0)
	v_lshl_add_u32 v0, v34, 2, 32
	s_movk_i32 s5, 0x480
	v_mad_u64_u32 v[2:3], s[8:9], v33, s5, v[0:1]
	s_movk_i32 s5, 0x120
	v_add_u32_e32 v1, 0x9000, v2
	v_cmp_gt_i32_e32 vcc, s5, v32
	ds_write2_b32 v1, v58, v59 offset1:32
	ds_write2_b32 v1, v60, v61 offset0:64 offset1:96
	ds_write2_b32 v1, v56, v57 offset0:128 offset1:160
	ds_write2_b32 v1, v54, v55 offset0:192 offset1:224
	ds_write_b32 v2, v63 offset:37888
	s_waitcnt lgkmcnt(0)
	s_barrier
	s_and_saveexec_b64 s[8:9], vcc
	s_cbranch_execz .LBB0_296
	s_load_dwordx2 s[28:29], s[0:1], 0x30
	s_load_dwordx2 s[34:35], s[0:1], 0xe0
	s_mul_i32 s5, s4, 0xc00
	s_add_i32 s40, s5, s6
	s_lshl_b64 s[6:7], s[6:7], 2
	v_or_b32_e32 v2, s40, v34
	s_waitcnt lgkmcnt(0)
	s_add_u32 s6, s34, s6
	s_addc_u32 s7, s35, s7
	v_ashrrev_i32_e32 v3, 31, v2
	v_lshlrev_b32_e32 v192, 2, v34
	s_mul_hi_i32 s5, s4, 9
	s_mul_i32 s4, s4, 9
	v_lshl_add_u64 v[2:3], v[2:3], 2, s[28:29]
	v_lshl_add_u64 v[4:5], s[6:7], 0, v[192:193]
	s_mov_b64 s[6:7], 0
